# FFN-in/FFN-out run as two row-halves each (hidden buffer half stays cache-resident between producer and consumer); V^T rounds reversed
# baseline (speedup 1.0000x reference)
_Z8yoco_fwd4Args:
	s_mov_b64 s[94:95], s[0:1]
	s_load_dword s0, s[0:1], 0x98
	v_and_b32_e32 v190, 0x3ff, v0
	v_cmp_gt_u32_e32 vcc, 8, v190
	s_waitcnt lgkmcnt(0)
	v_writelane_b32 v254, s0, 0
	s_mov_b64 s[0:1], s[94:95]
	s_load_dword s75, s[0:1], 0x9c
	s_and_saveexec_b64 s[4:5], vcc
	v_lshl_add_u32 v1, v190, 2, 0
	v_add_u32_e32 v1, 0x21000, v1
	v_mov_b32_e32 v2, 0
	ds_write_b32 v1, v2
	s_or_b64 exec, exec, s[4:5]
	v_readlane_b32 s0, v254, 0
	s_waitcnt lgkmcnt(0)
	s_movk_i32 s75, 24
	s_sub_i32 s0, s75, s0
	s_cmp_lt_i32 s0, 2
	s_cselect_b64 s[0:1], -1, 0
	s_cmp_lg_u32 s2, 0
	s_cselect_b64 s[4:5], -1, 0
	s_or_b64 s[0:1], s[4:5], s[0:1]
	s_mov_b32 s6, 0
	s_and_b64 vcc, exec, s[0:1]
	s_barrier
	s_cbranch_vccnz .LBB0_10
	s_mov_b64 s[0:1], s[94:95]
	s_load_dwordx2 s[0:1], s[0:1], 0x90
	v_sub_u32_e32 v1, 0xd7f, v190
	v_lshrrev_b32_e32 v2, 9, v1
	v_add_u32_e32 v1, 2, v2
	v_add_u32_e32 v191, 0x200, v190
	s_waitcnt lgkmcnt(0)
	s_add_u32 s8, s0, 0x200000
	v_and_b32_e32 v3, 14, v1
	s_addc_u32 s9, s1, 0
	v_mov_b32_e32 v1, v2
	s_mov_b64 s[10:11], 0
	s_mov_b32 s7, 1
	v_mov_b32_e32 v5, 0
	s_mov_b32 s12, s6
	v_mov_b64_e32 v[6:7], v[190:191]
	s_branch .LBB0_5

.LBB0_14:
	s_mov_b64 s[80:81], s[94:95]
	v_mov_b32_e32 v237, v190
	s_waitcnt lgkmcnt(0)
	s_load_dwordx2 s[78:79], s[80:81], 0x90
	s_load_dword s3, s[76:77], 0x0
	s_mov_b32 s72, s0
	s_and_b32 s47, s0, 7
	s_lshl_b32 s47, s47, 2
	s_mov_b32 s1, 0x54321210
	s_cmp_gt_u32 s0, 7
	s_cselect_b32 s1, 0x9a987656, s1
	s_cmp_gt_u32 s0, 15
	s_cselect_b32 s1, 0xfefedcba, s1
	s_lshr_b32 s1, s1, s47
	s_and_b32 s47, s1, 15
	s_lshr_b32 s100, 0xc18618, s0
	s_and_b32 s100, s100, 1
	s_lshl_b32 s100, s100, 9
	s_lshr_b32 s101, 0x204104, s0
	s_and_b32 s101, s101, 1
	s_lshl_b32 s101, s101, 9
	s_sub_u32 s101, 0x400, s101
	v_readlane_b32 s1, v254, 36
	s_lshr_b32 s0, s100, 5
	s_add_i32 s1, s1, s0
	v_writelane_b32 v254, s1, 62
	v_readfirstlane_b32 s74, v237
	v_and_b32_e32 v236, 63, v237
	s_mov_b64 s[6:7], -1
	s_mov_b64 s[48:49], 0
	s_cmp_lt_i32 s47, 8
	s_mov_b64 s[10:11], 0
	s_mov_b64 s[82:83], 0
	s_mov_b64 s[8:9], 0
	s_cbranch_scc1 .LBB0_64
	s_mov_b32 s73, s72
	s_mov_b32 s72, s86
	s_cmp_gt_i32 s47, 10
	s_cbranch_scc0 .LBB0_23
	s_mov_b64 s[8:9], -1
	s_mov_b64 s[86:87], 0
	s_cmp_gt_i32 s47, 11
	s_cbranch_scc0 .LBB0_24
	s_cmp_gt_i32 s47, 13
	s_cbranch_scc0 .LBB0_19
	s_cmp_eq_u32 s47, 14
	s_mov_b64 s[6:7], 0
	s_mov_b64 s[10:11], -1
	s_cselect_b64 s[82:83], -1, 0

.LBB0_142:
	s_and_b64 vcc, exec, s[82:83]
	s_cbranch_vccz .LBB0_166
	v_readlane_b32 s0, v254, 13
	v_readlane_b32 s1, v254, 14
	s_andn2_b64 vcc, exec, s[0:1]
	v_readfirstlane_b32 s83, v237
	s_cbranch_vccnz .LBB0_170
	s_cmp_eq_u32 s47, 1
	s_cselect_b64 s[14:15], -1, 0
	s_cmp_eq_u32 s47, 5
	s_cselect_b64 s[18:19], -1, 0
	s_or_b64 s[16:17], s[14:15], s[18:19]
	s_and_b64 s[0:1], s[16:17], exec
	s_cselect_b32 s0, 0, 0x100000
	s_waitcnt lgkmcnt(0)
	s_add_u32 s8, s78, s0
	s_addc_u32 s9, s79, 0
	s_ashr_i32 s0, s83, 6
	s_lshl_b32 s36, s0, 10
	s_cmp_lt_i32 s0, 4
	s_cselect_b64 s[10:11], -1, 0
	s_cmp_gt_i32 s0, 3
	s_cbranch_scc1 .LBB0_146
	s_and_b32 s1, s83, 0xffffffc0
	v_readlane_b32 s4, v254, 16
	s_lshl_b32 s20, s100, 3
	s_add_i32 s4, s4, s20
	s_add_i32 s20, s4, s1
	s_ashr_i32 s21, s20, 31
	s_lshl_b64 s[20:21], s[20:21], 4
	s_add_u32 s20, s8, s20
	s_addc_u32 s21, s9, s21
	s_add_i32 s1, s36, 0
	v_lshlrev_b32_e32 v0, 4, v236
	s_add_i32 m0, s1, 0x22000
	s_nop 0
	global_load_lds_dwordx4 v0, s[20:21]
.LBB0_146:
	v_ashrrev_i32_e32 v1, 31, v237
	v_lshrrev_b32_e32 v1, 26, v1
	v_add_u32_e32 v1, v237, v1
	v_ashrrev_i32_e32 v138, 6, v1
	v_bfe_i32 v1, v237, 27, 1
	v_lshlrev_b32_e32 v0, 4, v237
	v_lshrrev_b32_e32 v1, 22, v1
	v_add_u32_e32 v1, v0, v1
	s_cmp_eq_u32 s47, 9
	s_mov_b32 s1, 0x2100000
	v_and_b32_e32 v1, 0xfffffc00, v1
	s_cselect_b32 s1, 0x1600000, s1
	s_and_b64 s[18:19], s[18:19], exec
	v_sub_u32_e32 v1, v0, v1
	s_cselect_b32 s1, 0xb00000, s1
	s_and_b64 s[14:15], s[14:15], exec
	v_lshrrev_b32_e32 v2, 4, v1
	s_cselect_b32 s1, 0, s1
	s_and_b64 s[14:15], s[16:17], exec
	v_bitop3_b32 v1, v2, v1, 32 bitop3:0x6c
	s_cselect_b32 s4, 0x5000000, s66
	v_ashrrev_i32_e32 v3, 31, v1
	s_add_u32 s37, s78, s4
	v_lshrrev_b32_e32 v3, 26, v3
	s_addc_u32 s38, s79, 0
	v_add_u32_e32 v3, v1, v3
	s_add_u32 s1, s78, s1
	v_lshlrev_b32_e32 v2, 3, v138
	v_ashrrev_i32_e32 v139, 6, v3
	v_and_b32_e32 v3, 0xc0, v3
	s_addc_u32 s4, s79, 0
	v_and_b32_e32 v2, -16, v2
	v_sub_u32_e32 v1, v1, v3
	s_add_u32 s39, s1, 0x400000
	v_add_u32_e32 v2, v139, v2
	v_ashrrev_i16_sdwa v1, v227, sext(v1) dst_sel:DWORD dst_unused:UNUSED_PAD src0_sel:DWORD src1_sel:BYTE_0
	s_addc_u32 s40, s4, 0
	v_lshlrev_b32_e32 v4, 5, v138
	v_bfe_i32 v140, v1, 0, 16
	v_lshlrev_b32_e32 v1, 1, v2
	v_lshrrev_b32_e32 v3, 2, v2
	v_and_b32_e32 v5, 3, v139
	s_mov_b32 s4, 0x1fffe0
	v_and_b32_e32 v4, 32, v4
	v_and_b32_e32 v1, 24, v1
	v_and_b32_e32 v3, 4, v3
	v_and_or_b32 v5, v2, s4, v5
	v_or3_b32 v1, v5, v3, v1
	v_add_lshl_u32 v3, v4, v140, 1
	v_add_u32_e32 v0, 0x2000, v0
	v_lshl_add_u32 v48, v1, 11, v3
	v_ashrrev_i32_e32 v1, 31, v0
	v_lshrrev_b32_e32 v1, 22, v1
	v_add_u32_e32 v1, v0, v1
	v_ashrrev_i32_e32 v141, 10, v1
	v_mul_i32_i24_e32 v1, 0x400, v141
	v_sub_u32_e32 v0, v0, v1
	v_lshrrev_b32_e32 v1, 4, v0
	v_bitop3_b32 v0, v1, v0, 32 bitop3:0x6c
	v_lshl_add_u32 v154, v2, 11, v3
	v_ashrrev_i32_e32 v2, 31, v0
	v_lshrrev_b32_e32 v2, 26, v2
	v_add_u32_e32 v2, v0, v2
	v_lshlrev_b32_e32 v1, 3, v141
	v_ashrrev_i32_e32 v142, 6, v2
	v_and_b32_e32 v2, 0xc0, v2
	v_and_b32_e32 v1, -16, v1
	v_sub_u32_e32 v0, v0, v2
	s_ashr_i32 s1, s83, 8
	v_add_u32_e32 v1, v142, v1
	v_ashrrev_i16_sdwa v0, v227, sext(v0) dst_sel:DWORD dst_unused:UNUSED_PAD src0_sel:DWORD src1_sel:BYTE_0
	v_readlane_b32 s14, v254, 34
	v_lshlrev_b32_e32 v3, 5, v141
	v_bfe_i32 v143, v0, 0, 16
	v_lshlrev_b32_e32 v0, 1, v1
	v_lshrrev_b32_e32 v2, 2, v1
	v_and_b32_e32 v4, 3, v142
	v_readlane_b32 s15, v254, 35
	s_add_u32 s28, s39, s14
	v_and_b32_e32 v3, 32, v3
	v_and_b32_e32 v0, 24, v0
	v_and_b32_e32 v2, 4, v2
	v_and_or_b32 v4, v1, s4, v4
	s_addc_u32 s29, s40, s15
	s_add_i32 s41, s36, 0
	v_or3_b32 v0, v4, v2, v0
	v_add_lshl_u32 v2, v3, v143, 1
	s_add_i32 m0, s41, 0x10000
	v_lshl_add_u32 v156, v1, 11, v2
	v_lshl_add_u32 v158, v0, 11, v2
	v_mov_b64 v[122:123], 0
	v_mov_b64 v[124:125], 0
	v_mov_b64 v[114:115], 0
	v_mov_b64 v[116:117], 0
	v_mov_b64 v[106:107], 0
	v_mov_b64 v[108:109], 0
	v_mov_b64 v[98:99], 0
	v_mov_b64 v[100:101], 0
	v_mov_b64 v[90:91], 0
	v_mov_b64 v[92:93], 0
	v_mov_b64 v[82:83], 0
	v_mov_b64 v[84:85], 0
	v_mov_b64 v[74:75], 0
	v_mov_b64 v[76:77], 0
	v_mov_b64 v[66:67], 0
	v_mov_b64 v[68:69], 0
	v_mov_b64 v[130:131], 0
	v_mov_b64 v[132:133], 0
	v_mov_b64 v[118:119], 0
	v_mov_b64 v[120:121], 0
	v_mov_b64 v[110:111], 0
	v_mov_b64 v[112:113], 0
	v_mov_b64 v[102:103], 0
	v_mov_b64 v[104:105], 0
	v_mov_b64 v[94:95], 0
	v_mov_b64 v[96:97], 0
	v_mov_b64 v[86:87], 0
	v_mov_b64 v[88:89], 0
	v_mov_b64 v[78:79], 0
	v_mov_b64 v[80:81], 0
	v_mov_b64 v[70:71], 0
	v_mov_b64 v[72:73], 0
	v_mov_b64 v[58:59], 0
	v_mov_b64 v[60:61], 0
	v_mov_b64 v[50:51], 0
	v_mov_b64 v[52:53], 0
	v_mov_b64 v[40:41], 0
	v_mov_b64 v[42:43], 0
	v_mov_b64 v[32:33], 0
	v_mov_b64 v[34:35], 0
	v_mov_b64 v[24:25], 0
	v_mov_b64 v[26:27], 0
	v_mov_b64 v[16:17], 0
	v_mov_b64 v[18:19], 0
	v_mov_b64 v[8:9], 0
	v_mov_b64 v[10:11], 0
	v_mov_b64 v[0:1], 0
	v_mov_b64 v[2:3], 0
	v_mov_b64 v[62:63], 0
	v_mov_b64 v[64:65], 0
	v_mov_b64 v[54:55], 0
	v_mov_b64 v[56:57], 0
	v_mov_b64 v[44:45], 0
	v_mov_b64 v[46:47], 0
	v_mov_b64 v[36:37], 0
	v_mov_b64 v[38:39], 0
	v_mov_b64 v[28:29], 0
	v_mov_b64 v[30:31], 0
	v_mov_b64 v[20:21], 0
	v_mov_b64 v[22:23], 0
	v_mov_b64 v[12:13], 0
	v_mov_b64 v[14:15], 0
	v_mov_b64 v[4:5], 0
	v_mov_b64 v[6:7], 0
	global_load_lds_dwordx4 v48, s[28:29]
	s_add_i32 m0, s41, 0x12000
	s_add_u32 s14, s28, 0x40000
	global_load_lds_dwordx4 v158, s[28:29]
	s_addc_u32 s15, s29, 0
	s_add_i32 m0, s41, 0x14000
	v_mov_b32_e32 v159, v49
	global_load_lds_dwordx4 v48, s[14:15]
	s_add_i32 m0, s41, 0x16000
	v_mov_b32_e32 v155, v49
	global_load_lds_dwordx4 v158, s[14:15]
	v_readlane_b32 s14, v254, 30
	v_readlane_b32 s15, v254, 31
	s_lshl_b32 s30, s100, 14
	s_add_u32 s14, s14, s30
	s_addc_u32 s15, s15, 0
	s_add_u32 s30, s37, s14
	s_addc_u32 s31, s38, s15
	s_add_i32 s48, s41, 0x2000
	s_mov_b32 m0, s41
	s_add_u32 s14, s30, 0x40000
	global_load_lds_dwordx4 v154, s[30:31]
	s_mov_b32 m0, s48
	s_addc_u32 s15, s31, 0
	s_add_i32 s49, s41, 0x4000
	global_load_lds_dwordx4 v156, s[30:31]
	s_mov_b32 m0, s49
	s_add_i32 s50, s41, 0x6000
	global_load_lds_dwordx4 v154, s[14:15]
	s_mov_b32 m0, s50
	v_mov_b32_e32 v157, v49
	global_load_lds_dwordx4 v156, s[14:15]
	s_cmp_eq_u32 s1, 1
	v_lshl_add_u64 v[136:137], s[28:29], 0, v[48:49]
	v_lshl_add_u64 v[134:135], s[28:29], 0, v[158:159]
	v_lshl_add_u64 v[126:127], s[30:31], 0, v[154:155]
	s_cselect_b64 s[14:15], -1, 0
	s_cmp_lg_u32 s1, 1
	v_lshl_add_u64 v[128:129], s[30:31], 0, v[156:157]
	s_cbranch_scc1 .LBB0_148
	s_barrier
.LBB0_148:
	s_add_u32 s16, s78, 0x15000000
	s_addc_u32 s17, s79, 0
	s_lshl_b32 s0, s0, 5
	s_and_b32 s0, s0, 0x60
	s_add_i32 m0, s41, 0x18000
	v_lshl_add_u64 v[136:137], v[136:137], 0, s[70:71]
	s_lshl_b32 s4, s1, 13
	s_lshl_b32 s20, s0, 7
	s_waitcnt vmcnt(2)
	s_barrier
	global_load_lds_dwordx4 v[136:137], off
	v_lshl_add_u64 v[134:135], v[134:135], 0, s[70:71]
	s_add_i32 m0, s41, 0x1a000
	s_add_i32 s52, s41, 0x8000
	s_add_i32 s53, s41, 0xa000
	global_load_lds_dwordx4 v[134:135], off
	v_lshl_add_u64 v[126:127], v[126:127], 0, s[70:71]
	s_mov_b32 m0, s52
	s_add_u32 s18, s28, 0x40080
	global_load_lds_dwordx4 v[126:127], off
	v_lshl_add_u64 v[126:127], v[128:129], 0, s[70:71]
	s_mov_b32 m0, s53
	s_addc_u32 s19, s29, 0
	global_load_lds_dwordx4 v[126:127], off
	s_add_i32 m0, s41, 0x1c000
	v_lshl_add_u64 v[126:127], s[18:19], 0, v[48:49]
	global_load_lds_dwordx4 v[126:127], off
	v_lshl_add_u64 v[126:127], s[18:19], 0, v[158:159]
	s_add_i32 m0, s41, 0x1e000
	v_mov_b32_e32 v163, v49
	global_load_lds_dwordx4 v[126:127], off
	v_lshrrev_b32_e32 v127, 1, v237
	v_and_b32_e32 v128, 24, v127
	v_and_b32_e32 v126, 15, v237
	v_lshlrev_b32_e32 v127, 1, v128
	v_lshl_or_b32 v166, s1, 6, v126
	v_lshl_or_b32 v126, v126, 6, v127
	v_lshlrev_b32_e32 v127, 2, v237
	v_and_b32_e32 v127, 32, v127
	v_bitop3_b32 v129, v126, s4, v127 bitop3:0xde
	v_bitop3_b32 v167, s20, v126, v127 bitop3:0xf6
	v_lshlrev_b32_e32 v126, 4, v236
	v_mov_b32_e32 v127, v49
	v_lshl_add_u64 v[160:161], s[8:9], 0, v[126:127]
	v_lshlrev_b32_e32 v126, 14, v138
	v_and_b32_e32 v126, 0xffff8000, v126
	v_lshl_add_u32 v126, v139, 11, v126
	v_and_b32_e32 v127, 1, v138
	v_lshl_or_b32 v126, v127, 6, v126
	v_lshl_add_u32 v162, v140, 1, v126
	v_lshlrev_b32_e32 v126, 14, v141
	s_add_i32 s1, 0, 0x22000
	v_and_b32_e32 v126, 0xffff8000, v126
	v_readlane_b32 s8, v254, 32
	s_waitcnt vmcnt(6)
	s_add_i32 s82, s1, s36
	v_lshl_add_u32 v126, v142, 11, v126
	v_and_b32_e32 v127, 1, v141
	v_readlane_b32 s9, v254, 33
	s_cmpk_lt_u32 s83, 0x100
	v_or_b32_e32 v168, s0, v128
	v_lshl_or_b32 v126, v127, 6, v126
	s_mov_b32 s0, s8
	v_readlane_b32 s8, v254, 28
	s_cselect_b64 s[18:19], -1, 0
	s_andn2_b32 s83, s83, 63
	s_ashr_i32 s84, s3, 31
	v_lshl_add_u32 v169, v166, 4, s1
	v_lshl_add_u32 v164, v143, 1, v126
	v_mov_b32_e32 v165, v49
	s_mov_b32 s1, 0
	v_add_u32_e32 v170, 0, v129
	s_lshr_b32 s4, s100, 5
	s_add_i32 s4, s4, s8
	s_barrier
	v_readlane_b32 s9, v254, 29
	s_branch .LBB0_151

.LBB0_151:
	s_add_i32 s85, s1, 1
	s_lshr_b32 s8, s85, 1
	s_lshl_b32 s8, s8, 10
	s_and_b32 s9, s85, 1
	s_lshl_b32 s9, s9, 8
	s_add_i32 s8, s8, s9
	s_add_i32 s8, s8, s100
	s_lshr_b32 s9, s100, 1
	s_addk_i32 s9, 0x1400
	s_cmp_eq_u32 s85, 10
	s_cselect_b32 s8, s9, s8
	s_cmp_gt_u32 s85, 10
	s_cselect_b32 s8, 0x1600, s8
	s_add_u32 s24, s8, s2
	s_mov_b32 s25, 0
	v_mov_b64_e32 v[126:127], 0x1600
	v_cmp_gt_i64_e32 vcc, s[24:25], v[196:197]
	v_cmp_lt_i64_e64 s[8:9], s[24:25], v[126:127]
	s_cbranch_vccnz .LBB0_157
	s_ashr_i32 s22, s24, 3
	s_cmpk_gt_i32 s22, 0x27f
	s_mov_b64 s[20:21], -1
	s_cbranch_scc0 .LBB0_154
	s_add_i32 s20, s22, 0xfffffd80
	s_lshr_b32 s20, s20, 1
	s_and_b32 s20, s20, 0x7ffffff8
	s_bfe_u32 s21, s24, 0x30003
	s_or_b32 s23, s20, s21
	s_mov_b64 s[20:21], 0

.LBB0_180:
	s_cmp_eq_u32 s47, 13
	s_cselect_b64 s[12:13], -1, 0
	s_and_b64 s[0:1], s[12:13], exec
	s_cselect_b32 s4, 0x4c00000, s8
	s_cmp_eq_u32 s47, 4
	s_cselect_b64 s[10:11], -1, 0
	s_and_b64 s[0:1], s[10:11], exec
	s_mov_b32 s0, 0x15000000
	s_cselect_b32 s8, 0x5000000, s0
	s_cselect_b32 s4, 0x4e00000, s4
	s_or_b64 s[0:1], s[10:11], s[12:13]
	s_waitcnt lgkmcnt(0)
	s_add_u32 s36, s78, s8
	s_addc_u32 s37, s79, 0
	s_and_b64 s[14:15], s[0:1], exec
	s_cselect_b32 s8, 0, s9
	s_add_u32 s38, s78, s4
	s_addc_u32 s39, s79, s8
	s_and_b64 s[0:1], s[0:1], exec
	s_movk_i32 s0, 0xb00
	s_cselect_b32 s40, 0x400, s0
	s_cmp_eq_u32 s47, 10
	s_cselect_b64 s[0:1], -1, 0
	s_or_b64 s[8:9], s[10:11], s[0:1]
	s_cmp_eq_u32 s47, 15
	s_cselect_b64 s[0:1], -1, 0
	s_or_b64 s[0:1], s[0:1], s[8:9]
	s_and_b64 s[0:1], s[0:1], exec
	s_cselect_b32 s0, s66, 0x5000000
	s_add_u32 s16, s78, s0
	s_addc_u32 s17, s79, 0
	s_cmp_lg_u32 s47, 15
	s_mov_b64 s[14:15], -1
	s_cbranch_scc0 .LBB0_206
	s_and_b64 vcc, exec, s[6:7]
	v_readfirstlane_b32 s0, v237
	s_cbranch_vccnz .LBB0_205
	v_lshlrev_b32_e32 v238, 4, v237
	v_add_u32_e32 v0, 0x2000, v238
	v_ashrrev_i32_e32 v1, 31, v0
	v_lshrrev_b32_e32 v1, 22, v1
	v_add_u32_e32 v1, v0, v1
	v_ashrrev_i32_e32 v1, 10, v1
	v_mul_i32_i24_e32 v2, 0x400, v1
	v_sub_u32_e32 v0, v0, v2
	v_lshrrev_b32_e32 v2, 4, v0
	v_bitop3_b32 v0, v2, v0, 32 bitop3:0x6c
	s_and_b64 s[12:13], s[12:13], exec
	s_movk_i32 s1, 0xb00
	v_ashrrev_i32_e32 v2, 31, v0
	s_cselect_b32 s1, 0x400, s1
	s_and_b64 s[12:13], s[10:11], exec
	v_lshrrev_b32_e32 v2, 26, v2
	s_cselect_b32 s4, 0x100, s1
	s_ashr_i32 s12, s0, 6
	v_add_u32_e32 v2, v0, v2
	v_lshlrev_b32_e32 v4, 3, v1
	s_ashr_i32 s1, s0, 8
	s_lshl_b32 s50, s40, 8
	s_lshl_b32 s41, s4, 8
	s_lshl_b32 s48, s40, 9
	s_lshl_b32 s49, s4, 9
	s_lshl_b32 s52, s12, 10
	v_ashrrev_i32_e32 v3, 6, v2
	v_and_b32_e32 v4, -16, v4
	v_lshlrev_b32_e32 v1, 5, v1
	s_and_b64 s[10:11], s[10:11], exec
	v_add_u32_e32 v4, v3, v4
	v_and_b32_e32 v142, 32, v1
	v_and_b32_e32 v1, 0xc0, v2
	v_and_b32_e32 v3, 3, v3
	s_mov_b32 s10, 0xffffe0
	v_lshrrev_b32_e32 v5, 2, v4
	v_lshlrev_b32_e32 v6, 1, v4
	v_sub_u32_e32 v0, v0, v1
	v_and_or_b32 v3, v4, s10, v3
	v_and_b32_e32 v5, 4, v5
	v_and_b32_e32 v6, 24, v6
	v_ashrrev_i16_sdwa v0, v227, sext(v0) dst_sel:DWORD dst_unused:UNUSED_PAD src0_sel:DWORD src1_sel:BYTE_0
	v_or3_b32 v3, v3, v5, v6
	v_bfe_i32 v143, v0, 0, 16
	v_mul_u32_u24_e32 v3, s4, v3
	v_add_u32_e32 v0, v142, v143
	v_mul_lo_u32 v144, v4, s40
	v_add_lshl_u32 v198, v3, v0, 1
	v_add_lshl_u32 v200, v0, v144, 1
	v_bfe_i32 v0, v237, 27, 1
	v_lshrrev_b32_e32 v0, 22, v0
	v_add_u32_e32 v0, v238, v0
	v_and_b32_e32 v0, 0xfffffc00, v0
	v_sub_u32_e32 v0, v238, v0
	v_lshrrev_b32_e32 v1, 4, v0
	v_ashrrev_i32_e32 v3, 31, v237
	v_bitop3_b32 v0, v1, v0, 32 bitop3:0x6c
	v_lshrrev_b32_e32 v3, 26, v3
	v_ashrrev_i32_e32 v1, 31, v0
	v_add_u32_e32 v3, v237, v3
	v_lshrrev_b32_e32 v1, 26, v1
	v_ashrrev_i32_e32 v3, 6, v3
	v_add_u32_e32 v1, v0, v1
	v_lshlrev_b32_e32 v4, 3, v3
	v_ashrrev_i32_e32 v2, 6, v1
	v_and_b32_e32 v4, -16, v4
	v_add_u32_e32 v4, v2, v4
	v_and_b32_e32 v2, 3, v2
	v_and_or_b32 v2, v4, s10, v2
	v_readlane_b32 s10, v254, 62
	v_and_b32_e32 v1, 0xc0, v1
	v_readlane_b32 s11, v254, 37
	s_mov_b32 s14, s10
	s_cselect_b32 s53, 0x200, 0
	v_lshrrev_b32_e32 v5, 2, v4
	v_lshlrev_b32_e32 v6, 1, v4
	v_sub_u32_e32 v0, v0, v1
	s_mul_i32 s11, s48, s14
	v_readlane_b32 s14, v254, 38
	v_and_b32_e32 v5, 4, v5
	v_and_b32_e32 v6, 24, v6
	v_lshlrev_b32_e32 v3, 5, v3
	v_ashrrev_i16_sdwa v0, v227, sext(v0) dst_sel:DWORD dst_unused:UNUSED_PAD src0_sel:DWORD src1_sel:BYTE_0
	s_mul_i32 s13, s53, s14
	s_mul_i32 s14, s49, s14
	v_or3_b32 v2, v2, v5, v6
	v_and_b32_e32 v145, 32, v3
	v_bfe_i32 v146, v0, 0, 16
	s_add_u32 s30, s38, s14
	v_mul_u32_u24_e32 v2, s4, v2
	v_add_u32_e32 v0, v145, v146
	s_addc_u32 s31, s39, 0
	s_add_i32 s82, s52, 0
	v_add_lshl_u32 v48, v2, v0, 1
	v_mul_lo_u32 v147, v4, s40
	s_add_i32 m0, s82, 0x10000
	v_add_lshl_u32 v202, v0, v147, 1
	v_mov_b64 v[126:127], 0
	v_mov_b64 v[128:129], 0
	v_mov_b64 v[122:123], 0
	v_mov_b64 v[124:125], 0
	v_mov_b64 v[110:111], 0
	v_mov_b64 v[112:113], 0
	v_mov_b64 v[98:99], 0
	v_mov_b64 v[100:101], 0
	v_mov_b64 v[94:95], 0
	v_mov_b64 v[96:97], 0
	v_mov_b64 v[82:83], 0
	v_mov_b64 v[84:85], 0
	v_mov_b64 v[78:79], 0
	v_mov_b64 v[80:81], 0
	v_mov_b64 v[66:67], 0
	v_mov_b64 v[68:69], 0
	v_mov_b64 v[118:119], 0
	v_mov_b64 v[120:121], 0
	v_mov_b64 v[114:115], 0
	v_mov_b64 v[116:117], 0
	v_mov_b64 v[106:107], 0
	v_mov_b64 v[108:109], 0
	v_mov_b64 v[102:103], 0
	v_mov_b64 v[104:105], 0
	v_mov_b64 v[90:91], 0
	v_mov_b64 v[92:93], 0
	v_mov_b64 v[86:87], 0
	v_mov_b64 v[88:89], 0
	v_mov_b64 v[74:75], 0
	v_mov_b64 v[76:77], 0
	v_mov_b64 v[70:71], 0
	v_mov_b64 v[72:73], 0
	v_mov_b64 v[62:63], 0
	v_mov_b64 v[64:65], 0
	v_mov_b64 v[50:51], 0
	v_mov_b64 v[52:53], 0
	v_mov_b64 v[44:45], 0
	v_mov_b64 v[46:47], 0
	v_mov_b64 v[32:33], 0
	v_mov_b64 v[34:35], 0
	v_mov_b64 v[28:29], 0
	v_mov_b64 v[30:31], 0
	v_mov_b64 v[16:17], 0
	v_mov_b64 v[18:19], 0
	v_mov_b64 v[12:13], 0
	v_mov_b64 v[14:15], 0
	v_mov_b64 v[0:1], 0
	v_mov_b64 v[2:3], 0
	v_mov_b64 v[58:59], 0
	v_mov_b64 v[60:61], 0
	v_mov_b64 v[54:55], 0
	v_mov_b64 v[56:57], 0
	v_mov_b64 v[40:41], 0
	v_mov_b64 v[42:43], 0
	v_mov_b64 v[36:37], 0
	v_mov_b64 v[38:39], 0
	v_mov_b64 v[24:25], 0
	v_mov_b64 v[26:27], 0
	v_mov_b64 v[20:21], 0
	v_mov_b64 v[22:23], 0
	v_mov_b64 v[8:9], 0
	v_mov_b64 v[10:11], 0
	v_mov_b64 v[4:5], 0
	v_mov_b64 v[6:7], 0
	global_load_lds_dwordx4 v48, s[30:31]
	s_add_i32 m0, s82, 0x12000
	s_mul_hi_i32 s10, s48, s10
	s_add_u32 s14, s36, s11
	s_addc_u32 s15, s37, s10
	s_add_u32 s10, s30, s41
	global_load_lds_dwordx4 v198, s[30:31]
	s_addc_u32 s11, s31, 0
	s_add_i32 m0, s82, 0x14000
	v_mov_b32_e32 v199, v49
	global_load_lds_dwordx4 v48, s[10:11]
	s_add_i32 m0, s82, 0x16000
	s_add_u32 s34, s14, s13
	s_addc_u32 s35, s15, 0
	s_add_i32 s83, s82, 0x2000
	v_lshl_add_u64 v[134:135], s[10:11], 0, v[48:49]
	v_lshl_add_u64 v[136:137], s[10:11], 0, v[198:199]
	global_load_lds_dwordx4 v198, s[10:11]
	s_mov_b32 m0, s82
	s_add_u32 s10, s34, s50
	global_load_lds_dwordx4 v202, s[34:35]
	s_mov_b32 m0, s83
	s_addc_u32 s11, s35, 0
	s_add_i32 s84, s82, 0x4000
	global_load_lds_dwordx4 v200, s[34:35]
	s_mov_b32 m0, s84
	s_add_i32 s85, s82, 0x6000
	global_load_lds_dwordx4 v202, s[10:11]
	s_mov_b32 m0, s85
	v_mov_b32_e32 v203, v49
	global_load_lds_dwordx4 v200, s[10:11]
	v_mov_b32_e32 v201, v49
	s_cmp_eq_u32 s1, 1
	s_mov_b32 s54, s86
	v_lshl_add_u64 v[130:131], s[30:31], 0, v[48:49]
	v_lshl_add_u64 v[132:133], s[30:31], 0, v[198:199]
	v_lshl_add_u64 v[138:139], s[34:35], 0, v[202:203]
	v_lshl_add_u64 v[140:141], s[34:35], 0, v[200:201]
	s_cselect_b64 s[18:19], -1, 0
	s_cmp_lg_u32 s1, 1
	s_cbranch_scc1 .LBB0_184
	s_barrier
.LBB0_184:
	s_and_b64 s[10:11], s[8:9], exec
	s_cselect_b32 s10, 0x5000000, s66
	s_add_u32 s20, s78, s10
	s_addc_u32 s21, s79, 0
	s_and_b64 s[8:9], s[8:9], exec
	s_cselect_b32 s8, 0, 0x100000
	s_add_u32 s22, s78, s8
	s_addc_u32 s23, s79, 0
	s_add_i32 m0, s82, 0x18000
	v_lshl_add_u64 v[130:131], v[130:131], 0, s[70:71]
	s_waitcnt vmcnt(2)
	s_barrier
	global_load_lds_dwordx4 v[130:131], off
	v_lshl_add_u64 v[130:131], v[132:133], 0, s[70:71]
	s_add_i32 m0, s82, 0x1a000
	s_add_i32 s86, s82, 0x8000
	global_load_lds_dwordx4 v[130:131], off
	v_lshl_add_u64 v[130:131], v[138:139], 0, s[70:71]
	s_mov_b32 m0, s86
	s_add_i32 s87, s82, 0xa000
	global_load_lds_dwordx4 v[130:131], off
	v_lshl_add_u64 v[130:131], v[140:141], 0, s[70:71]
	s_mov_b32 m0, s87
	s_and_b32 s10, s12, 3
	global_load_lds_dwordx4 v[130:131], off
	s_add_i32 m0, s82, 0x1c000
	v_lshl_add_u64 v[130:131], v[134:135], 0, s[70:71]
	global_load_lds_dwordx4 v[130:131], off
	v_lshl_add_u64 v[130:131], v[136:137], 0, s[70:71]
	s_add_i32 m0, s82, 0x1e000
	v_lshlrev_b32_e32 v134, 2, v237
	global_load_lds_dwordx4 v[130:131], off
	v_bfe_u32 v130, v237, 4, 2
	v_and_b32_e32 v131, 15, v237
	v_lshlrev_b32_e32 v133, 4, v130
	s_lshr_b32 s89, s4, 6
	s_lshl_b32 s4, s1, 6
	v_lshl_or_b32 v133, v131, 6, v133
	s_lshl_b32 s1, s1, 13
	v_and_b32_e32 v134, 32, v134
	v_bitop3_b32 v135, v133, s1, v134 bitop3:0xde
	s_lshl_b32 s1, s10, 12
	s_add_i32 s90, s89, -2
	s_cmpk_lt_u32 s0, 0x100
	v_bitop3_b32 v240, s1, v133, v134 bitop3:0xf6
	s_cselect_b64 s[24:25], -1, 0
	s_add_i32 s1, s4, 0x80
	v_lshlrev_b32_e32 v132, 3, v130
	v_cmp_eq_u32_e64 s[8:9], 0, v130
	v_or_b32_e32 v130, s1, v131
	s_add_i32 s1, s4, 0x90
	v_lshlrev_b32_e32 v133, 4, v130
	v_or_b32_e32 v130, s1, v131
	s_add_i32 s1, s4, 0xa0
	v_or_b32_e32 v239, s4, v131
	v_lshlrev_b32_e32 v134, 4, v130
	v_or_b32_e32 v130, s1, v131
	s_addk_i32 s4, 0xb0
	v_lshlrev_b32_e32 v136, 4, v130
	v_or_b32_e32 v130, s4, v131
	s_lshl_b32 s0, s10, 2
	v_lshlrev_b32_e32 v137, 4, v130
	v_add_u32_e32 v130, v147, v145
	s_add_i32 s0, s0, 0
	v_add_lshl_u32 v130, v130, v146, 1
	v_mov_b32_e32 v131, v49
	s_waitcnt vmcnt(6)
	v_lshl_or_b32 v241, s10, 5, v132
	s_add_i32 s0, s0, 0x20000
	v_lshlrev_b32_e32 v132, 4, v239
	v_lshl_add_u64 v[204:205], s[50:51], 0, v[130:131]
	v_add_u32_e32 v130, v144, v142
	s_movk_i32 s1, 0x100
	v_add_lshl_u32 v130, v130, v143, 1
	v_add_u32_e32 v243, s0, v132
	v_add_u32_e32 v244, s0, v133
	v_add_u32_e32 v245, s0, v134
	v_add_u32_e32 v246, s0, v136
	v_add_u32_e32 v247, s0, v137
	v_readlane_b32 s0, v254, 38
	s_mov_b32 s88, 0
	v_cmp_gt_i32_e64 s[10:11], s1, v237
	s_ashr_i32 s91, s3, 31
	v_lshl_add_u64 v[206:207], s[50:51], 0, v[130:131]
	v_add_u32_e32 v242, 0, v135
	s_mov_b32 s26, s0
	v_readlane_b32 s0, v254, 62
	s_barrier
	v_readlane_b32 s1, v254, 37
	s_branch .LBB0_187

.LBB0_187:
	s_add_i32 s88, s88, 1
	s_mul_i32 s1, s88, s91
	s_mul_hi_u32 s4, s88, s3
	s_add_i32 s4, s4, s1
	s_mul_i32 s1, s88, s3
	s_add_u32 s12, s1, s2
	s_addc_u32 s13, s4, s5
	s_add_u32 s12, s12, s100
	s_addc_u32 s13, s13, 0
	s_cmp_ge_u32 s12, s101
	s_cselect_b32 s12, 0x400, s12
	v_cmp_gt_i64_e32 vcc, s[12:13], v[194:195]
	v_cmp_lt_i64_e64 s[14:15], s[12:13], v[192:193]
	s_cbranch_vccnz .LBB0_189
	s_lshl_b32 s1, s12, 7
	s_and_b32 s1, s1, 0x380
	s_ashr_i32 s4, s12, 3
	s_add_i32 s1, s1, s4
	s_ashr_i32 s1, s1, 2
	s_and_b32 s1, s1, -8
	s_and_b32 s12, s4, 7
	s_or_b32 s93, s1, s12
	s_bfe_u32 s92, s4, 0x20003

.LBB0_206:
	s_andn2_b64 vcc, exec, s[14:15]
	s_cbranch_vccnz .LBB0_227
	s_and_b64 vcc, exec, s[6:7]
	v_readfirstlane_b32 s0, v237
	s_cbranch_vccnz .LBB0_227
	v_lshlrev_b32_e32 v0, 4, v237
	v_add_u32_e32 v1, 0x2000, v0
	v_ashrrev_i32_e32 v2, 31, v1
	v_lshrrev_b32_e32 v2, 22, v2
	v_add_u32_e32 v2, v1, v2
	v_ashrrev_i32_e32 v2, 10, v2
	v_mul_i32_i24_e32 v3, 0x400, v2
	v_sub_u32_e32 v1, v1, v3
	v_lshrrev_b32_e32 v3, 4, v1
	v_bitop3_b32 v1, v3, v1, 32 bitop3:0x6c
	v_ashrrev_i32_e32 v3, 31, v1
	v_lshrrev_b32_e32 v3, 26, v3
	v_add_u32_e32 v3, v1, v3
	v_lshlrev_b32_e32 v5, 3, v2
	v_ashrrev_i32_e32 v4, 6, v3
	v_and_b32_e32 v5, -16, v5
	v_lshlrev_b32_e32 v2, 5, v2
	v_add_u32_e32 v5, v4, v5
	v_and_b32_e32 v138, 32, v2
	v_and_b32_e32 v2, 0xc0, v3
	v_and_b32_e32 v4, 3, v4
	s_mov_b32 s6, 0xffffe0
	v_lshrrev_b32_e32 v6, 2, v5
	v_lshlrev_b32_e32 v7, 1, v5
	v_sub_u32_e32 v1, v1, v2
	v_and_or_b32 v4, v5, s6, v4
	v_and_b32_e32 v6, 4, v6
	v_and_b32_e32 v7, 24, v7
	v_ashrrev_i16_sdwa v1, v227, sext(v1) dst_sel:DWORD dst_unused:UNUSED_PAD src0_sel:DWORD src1_sel:BYTE_0
	v_or3_b32 v4, v4, v6, v7
	v_bfe_i32 v139, v1, 0, 16
	v_mul_u32_u24_e32 v4, 0xb00, v4
	v_add_u32_e32 v1, v138, v139
	v_mul_lo_u32 v140, v5, s40
	v_add_lshl_u32 v198, v4, v1, 1
	v_add_lshl_u32 v200, v1, v140, 1
	v_bfe_i32 v1, v237, 27, 1
	v_lshrrev_b32_e32 v1, 22, v1
	v_add_u32_e32 v1, v0, v1
	v_and_b32_e32 v1, 0xfffffc00, v1
	v_sub_u32_e32 v0, v0, v1
	v_lshrrev_b32_e32 v1, 4, v0
	v_ashrrev_i32_e32 v3, 31, v237
	v_bitop3_b32 v0, v1, v0, 32 bitop3:0x6c
	v_lshrrev_b32_e32 v3, 26, v3
	v_ashrrev_i32_e32 v1, 31, v0
	v_add_u32_e32 v3, v237, v3
	v_lshrrev_b32_e32 v1, 26, v1
	v_ashrrev_i32_e32 v3, 6, v3
	v_add_u32_e32 v1, v0, v1
	v_lshlrev_b32_e32 v4, 3, v3
	v_ashrrev_i32_e32 v2, 6, v1
	v_and_b32_e32 v4, -16, v4
	v_add_u32_e32 v4, v2, v4
	v_and_b32_e32 v2, 3, v2
	v_and_or_b32 v2, v4, s6, v2
	v_readlane_b32 s6, v254, 62
	s_lshl_b32 s28, s40, 9
	v_and_b32_e32 v1, 0xc0, v1
	v_readlane_b32 s7, v254, 37
	s_mov_b32 s8, s6
	s_ashr_i32 s4, s0, 6
	v_lshrrev_b32_e32 v5, 2, v4
	v_lshlrev_b32_e32 v6, 1, v4
	v_sub_u32_e32 v0, v0, v1
	s_mul_i32 s7, s28, s8
	v_readlane_b32 s8, v254, 38
	s_ashr_i32 s1, s0, 8
	s_lshl_b32 s50, s40, 8
	s_lshl_b32 s29, s4, 10
	v_and_b32_e32 v5, 4, v5
	v_and_b32_e32 v6, 24, v6
	v_lshlrev_b32_e32 v3, 5, v3
	v_ashrrev_i16_sdwa v0, v227, sext(v0) dst_sel:DWORD dst_unused:UNUSED_PAD src0_sel:DWORD src1_sel:BYTE_0
	s_mul_i32 s8, s8, 0x160000
	v_or3_b32 v2, v2, v5, v6
	v_and_b32_e32 v141, 32, v3
	v_bfe_i32 v142, v0, 0, 16
	s_add_u32 s22, s38, s8
	v_mul_u32_u24_e32 v2, 0xb00, v2
	v_add_u32_e32 v0, v141, v142
	s_addc_u32 s23, s39, 0
	s_add_i32 s30, s29, 0
	v_add_lshl_u32 v48, v2, v0, 1
	v_mul_lo_u32 v143, v4, s40
	s_add_i32 m0, s30, 0x10000
	s_load_dwordx2 s[10:11], s[80:81], 0x88
	v_add_lshl_u32 v202, v0, v143, 1
	v_mov_b64 v[126:127], 0
	v_mov_b64 v[128:129], 0
	v_mov_b64 v[122:123], 0
	v_mov_b64 v[124:125], 0
	v_mov_b64 v[110:111], 0
	v_mov_b64 v[112:113], 0
	v_mov_b64 v[102:103], 0
	v_mov_b64 v[104:105], 0
	v_mov_b64 v[94:95], 0
	v_mov_b64 v[96:97], 0
	v_mov_b64 v[86:87], 0
	v_mov_b64 v[88:89], 0
	v_mov_b64 v[78:79], 0
	v_mov_b64 v[80:81], 0
	v_mov_b64 v[70:71], 0
	v_mov_b64 v[72:73], 0
	v_mov_b64 v[118:119], 0
	v_mov_b64 v[120:121], 0
	v_mov_b64 v[114:115], 0
	v_mov_b64 v[116:117], 0
	v_mov_b64 v[106:107], 0
	v_mov_b64 v[108:109], 0
	v_mov_b64 v[98:99], 0
	v_mov_b64 v[100:101], 0
	v_mov_b64 v[90:91], 0
	v_mov_b64 v[92:93], 0
	v_mov_b64 v[82:83], 0
	v_mov_b64 v[84:85], 0
	v_mov_b64 v[74:75], 0
	v_mov_b64 v[76:77], 0
	v_mov_b64 v[66:67], 0
	v_mov_b64 v[68:69], 0
	v_mov_b64 v[62:63], 0
	v_mov_b64 v[64:65], 0
	v_mov_b64 v[54:55], 0
	v_mov_b64 v[56:57], 0
	v_mov_b64 v[44:45], 0
	v_mov_b64 v[46:47], 0
	v_mov_b64 v[36:37], 0
	v_mov_b64 v[38:39], 0
	v_mov_b64 v[28:29], 0
	v_mov_b64 v[30:31], 0
	v_mov_b64 v[20:21], 0
	v_mov_b64 v[22:23], 0
	s_waitcnt lgkmcnt(0)
	v_mov_b64 v[12:13], 0
	v_mov_b64 v[14:15], 0
	v_mov_b64 v[0:1], 0
	v_mov_b64 v[2:3], 0
	v_mov_b64 v[58:59], 0
	v_mov_b64 v[60:61], 0
	v_mov_b64 v[50:51], 0
	v_mov_b64 v[52:53], 0
	v_mov_b64 v[40:41], 0
	v_mov_b64 v[42:43], 0
	v_mov_b64 v[32:33], 0
	v_mov_b64 v[34:35], 0
	v_mov_b64 v[24:25], 0
	v_mov_b64 v[26:27], 0
	v_mov_b64 v[16:17], 0
	v_mov_b64 v[18:19], 0
	v_mov_b64 v[8:9], 0
	v_mov_b64 v[10:11], 0
	v_mov_b64 v[4:5], 0
	v_mov_b64 v[6:7], 0
	global_load_lds_dwordx4 v48, s[22:23]
	s_add_i32 m0, s30, 0x12000
	s_mul_hi_i32 s6, s28, s6
	s_add_u32 s20, s36, s7
	s_addc_u32 s21, s37, s6
	s_add_u32 s6, s22, 0xb0000
	global_load_lds_dwordx4 v198, s[22:23]
	s_addc_u32 s7, s23, 0
	s_add_i32 m0, s30, 0x14000
	s_add_i32 s31, s30, 0x2000
	global_load_lds_dwordx4 v48, s[6:7]
	s_add_i32 m0, s30, 0x16000
	v_mov_b32_e32 v199, v49
	global_load_lds_dwordx4 v198, s[6:7]
	s_mov_b32 m0, s30
	s_add_u32 s6, s20, s50
	global_load_lds_dwordx4 v202, s[20:21]
	s_mov_b32 m0, s31
	s_addc_u32 s7, s21, 0
	s_add_i32 s34, s30, 0x4000
	global_load_lds_dwordx4 v200, s[20:21]
	s_mov_b32 m0, s34
	s_add_i32 s35, s30, 0x6000
	global_load_lds_dwordx4 v202, s[6:7]
	s_mov_b32 m0, s35
	v_mov_b32_e32 v203, v49
	global_load_lds_dwordx4 v200, s[6:7]
	v_mov_b32_e32 v201, v49
	s_cmp_eq_u32 s1, 1
	v_lshl_add_u64 v[136:137], s[22:23], 0, v[48:49]
	v_lshl_add_u64 v[134:135], s[22:23], 0, v[198:199]
	v_lshl_add_u64 v[130:131], s[20:21], 0, v[202:203]
	s_cselect_b64 s[12:13], -1, 0
	s_cmp_lg_u32 s1, 1
	v_lshl_add_u64 v[132:133], s[20:21], 0, v[200:201]
	s_cbranch_scc1 .LBB0_210
	s_barrier
.LBB0_210:
	s_lshl_b32 s4, s4, 5
	s_and_b32 s4, s4, 0x60
	s_add_i32 m0, s30, 0x18000
	v_lshl_add_u64 v[136:137], v[136:137], 0, s[70:71]
	s_lshl_b32 s8, s1, 13
	s_lshl_b32 s9, s4, 7
	s_waitcnt vmcnt(2)
	s_barrier
	global_load_lds_dwordx4 v[136:137], off
	v_lshl_add_u64 v[134:135], v[134:135], 0, s[70:71]
	s_add_i32 m0, s30, 0x1a000
	s_add_i32 s40, s30, 0x8000
	s_add_i32 s41, s30, 0xa000
	global_load_lds_dwordx4 v[134:135], off
	v_lshl_add_u64 v[130:131], v[130:131], 0, s[70:71]
	s_mov_b32 m0, s40
	s_add_u32 s6, s22, 0xb0080
	global_load_lds_dwordx4 v[130:131], off
	v_lshl_add_u64 v[130:131], v[132:133], 0, s[70:71]
	s_mov_b32 m0, s41
	s_addc_u32 s7, s23, 0
	global_load_lds_dwordx4 v[130:131], off
	s_add_i32 m0, s30, 0x1c000
	v_lshl_add_u64 v[130:131], s[6:7], 0, v[48:49]
	global_load_lds_dwordx4 v[130:131], off
	v_lshl_add_u64 v[130:131], s[6:7], 0, v[198:199]
	s_add_i32 m0, s30, 0x1e000
	s_cmpk_lt_u32 s0, 0x100
	global_load_lds_dwordx4 v[130:131], off
	v_lshrrev_b32_e32 v131, 1, v237
	v_and_b32_e32 v131, 24, v131
	v_and_b32_e32 v130, 15, v237
	v_lshlrev_b32_e32 v132, 1, v131
	v_lshl_or_b32 v238, s1, 6, v130
	v_lshl_or_b32 v130, v130, 6, v132
	v_lshlrev_b32_e32 v132, 2, v237
	v_and_b32_e32 v132, 32, v132
	v_bitop3_b32 v133, v130, s8, v132 bitop3:0xde
	v_bitop3_b32 v239, s9, v130, v132 bitop3:0xf6
	v_add_u32_e32 v130, v143, v141
	v_or_b32_e32 v240, s4, v131
	v_add_lshl_u32 v130, v130, v142, 1
	v_mov_b32_e32 v131, v49
	s_waitcnt vmcnt(6)
	v_lshl_add_u64 v[204:205], s[50:51], 0, v[130:131]
	v_add_u32_e32 v130, v140, v138
	v_add_lshl_u32 v130, v130, v139, 1
	v_readlane_b32 s6, v254, 62
	s_cselect_b64 s[14:15], -1, 0
	s_ashr_i32 s48, s3, 31
	v_lshl_add_u64 v[206:207], s[50:51], 0, v[130:131]
	s_mov_b32 s49, 0
	v_add_u32_e32 v241, 0, v133
	v_readlane_b32 s0, v254, 38
	s_mov_b32 s1, s6
	s_barrier
	v_readlane_b32 s7, v254, 37
	s_branch .LBB0_213

.LBB0_213:
	s_add_i32 s49, s49, 1
	s_mul_i32 s4, s49, s48
	s_mul_hi_u32 s6, s49, s3
	s_add_i32 s4, s6, s4
	s_mul_i32 s6, s49, s3
	s_add_u32 s6, s6, s2
	s_addc_u32 s7, s4, s5
	s_add_u32 s6, s6, s100
	s_addc_u32 s7, s7, 0
	s_cmp_ge_u32 s6, s101
	s_cselect_b32 s6, 0x400, s6
	v_cmp_gt_i64_e32 vcc, s[6:7], v[194:195]
	v_cmp_lt_i64_e64 s[8:9], s[6:7], v[192:193]
	s_cbranch_vccnz .LBB0_215
	s_lshl_b32 s4, s6, 7
	s_and_b32 s4, s4, 0x380
	s_ashr_i32 s6, s6, 3
	s_add_i32 s4, s4, s6
	s_ashr_i32 s4, s4, 2
	s_and_b32 s4, s4, -8
	s_and_b32 s7, s6, 7
	s_or_b32 s53, s4, s7
	s_bfe_u32 s52, s6, 0x20003

	.amdhsa_kernel _Z8yoco_fwd4Args
		.amdhsa_group_segment_fixed_size 0
		.amdhsa_private_segment_fixed_size 0
		.amdhsa_kernarg_size 416
		.amdhsa_user_sgpr_count 2
		.amdhsa_user_sgpr_dispatch_ptr 0
		.amdhsa_user_sgpr_queue_ptr 0
		.amdhsa_user_sgpr_kernarg_segment_ptr 1
		.amdhsa_user_sgpr_dispatch_id 0
		.amdhsa_user_sgpr_kernarg_preload_length 0
		.amdhsa_user_sgpr_kernarg_preload_offset 0
		.amdhsa_user_sgpr_private_segment_size 0
		.amdhsa_uses_dynamic_stack 0
		.amdhsa_enable_private_segment 0
		.amdhsa_system_sgpr_workgroup_id_x 1
		.amdhsa_system_sgpr_workgroup_id_y 0
		.amdhsa_system_sgpr_workgroup_id_z 0
		.amdhsa_system_sgpr_workgroup_info 0
		.amdhsa_system_vgpr_workitem_id 2
		.amdhsa_next_free_vgpr 255
		.amdhsa_next_free_sgpr 102
		.amdhsa_accum_offset 256
		.amdhsa_reserve_vcc 1
		.amdhsa_float_round_mode_32 0
		.amdhsa_float_round_mode_16_64 0
		.amdhsa_float_denorm_mode_32 3
		.amdhsa_float_denorm_mode_16_64 3
		.amdhsa_dx10_clamp 1
		.amdhsa_ieee_mode 1
		.amdhsa_fp16_overflow 0
		.amdhsa_tg_split 0
		.amdhsa_exception_fp_ieee_invalid_op 0
		.amdhsa_exception_fp_denorm_src 0
		.amdhsa_exception_fp_ieee_div_zero 0
		.amdhsa_exception_fp_ieee_overflow 0
		.amdhsa_exception_fp_ieee_underflow 0
		.amdhsa_exception_fp_ieee_inexact 0
		.amdhsa_exception_int_div_zero 0
	.end_amdhsa_kernel

amdhsa.kernels:
  - .agpr_count:     0
    .args:
      - .offset:         0
        .size:           160
        .value_kind:     by_value
      - .offset:         160
        .size:           4
        .value_kind:     hidden_block_count_x
      - .offset:         164
        .size:           4
        .value_kind:     hidden_block_count_y
      - .offset:         168
        .size:           4
        .value_kind:     hidden_block_count_z
      - .offset:         172
        .size:           2
        .value_kind:     hidden_group_size_x
      - .offset:         174
        .size:           2
        .value_kind:     hidden_group_size_y
      - .offset:         176
        .size:           2
        .value_kind:     hidden_group_size_z
      - .offset:         178
        .size:           2
        .value_kind:     hidden_remainder_x
      - .offset:         180
        .size:           2
        .value_kind:     hidden_remainder_y
      - .offset:         182
        .size:           2
        .value_kind:     hidden_remainder_z
      - .offset:         200
        .size:           8
        .value_kind:     hidden_global_offset_x
      - .offset:         208
        .size:           8
        .value_kind:     hidden_global_offset_y
      - .offset:         216
        .size:           8
        .value_kind:     hidden_global_offset_z
      - .offset:         224
        .size:           2
        .value_kind:     hidden_grid_dims
      - .offset:         248
        .size:           8
        .value_kind:     hidden_multigrid_sync_arg
      - .offset:         280
        .size:           4
        .value_kind:     hidden_dynamic_lds_size
    .group_segment_fixed_size: 0
    .kernarg_segment_align: 8
    .kernarg_segment_size: 416
    .language:       OpenCL C
    .language_version:
      - 2
      - 0
    .max_flat_workgroup_size: 512
    .name:           _Z8yoco_fwd4Args
    .private_segment_fixed_size: 0
    .sgpr_count:     108
    .sgpr_spill_count: 61
    .symbol:         _Z8yoco_fwd4Args.kd
    .uniform_work_group_size: 1
    .uses_dynamic_stack: false
    .vgpr_count:     255
    .vgpr_spill_count: 0
    .wavefront_size: 64
